# gdn_prep triangular solve: each L-row LDS read issued one row earlier into alternating free register slots (overlaps previous row's fma chain)
# speedup vs baseline: 1.0034x; 1.0020x over previous
.LBB0_363:
	s_or_b64 exec, exec, vcc
	s_waitcnt lgkmcnt(0)
	s_barrier
	ds_read_b32 v86, v167 offset:144
	s_waitcnt lgkmcnt(0)
	ds_read_b32 v242, v167 offset:288
	v_lshlrev_b32_e32 v86, 16, v86
	v_fma_f32 v1, -v0, v86, v1
	s_nop 0
	s_waitcnt lgkmcnt(0)
	ds_read_b128 v[232:235], v167 offset:432
	v_lshlrev_b32_e32 v86, 16, v242
	v_and_b32_e32 v87, 0xffff0000, v242
	v_pk_mul_f32 v[86:87], v[0:1], v[86:87]
	s_nop 0
	v_sub_f32_e32 v2, v2, v86
	v_sub_f32_e32 v87, v2, v87
	s_nop 0
	v_mov_b32_e32 v86, v1
	s_waitcnt lgkmcnt(0)
	ds_read_b64 v[242:243], v167 offset:576
	v_lshlrev_b32_e32 v2, 16, v232
	v_and_b32_e32 v94, 0xffff0000, v232
	v_lshlrev_b32_e32 v95, 16, v233
	v_fma_f32 v96, -v0, v2, v3
	v_pk_mul_f32 v[2:3], v[86:87], v[94:95]
	s_nop 0
	v_sub_f32_e32 v2, v96, v2
	v_sub_f32_e32 v3, v2, v3
	s_nop 0
	v_mov_b32_e32 v2, v87
	s_waitcnt lgkmcnt(0)
	ds_read_b128 v[232:235], v167 offset:720
	v_lshlrev_b32_e32 v96, 16, v242
	v_and_b32_e32 v97, 0xffff0000, v242
	v_pk_mul_f32 v[96:97], v[0:1], v[96:97]
	v_lshlrev_b32_e32 v94, 16, v243
	v_and_b32_e32 v95, 0xffff0000, v243
	v_sub_f32_e32 v4, v4, v96
	v_pk_mul_f32 v[94:95], v[2:3], v[94:95]
	v_sub_f32_e32 v4, v4, v97
	v_sub_f32_e32 v4, v4, v94
	v_sub_f32_e32 v95, v4, v95
	s_nop 0
	s_waitcnt lgkmcnt(0)
	ds_read_b96 v[242:244], v167 offset:864
	v_lshlrev_b32_e32 v4, 16, v232
	v_and_b32_e32 v96, 0xffff0000, v232
	v_lshlrev_b32_e32 v97, 16, v233
	v_fma_f32 v94, -v0, v4, v5
	v_pk_mul_f32 v[4:5], v[86:87], v[96:97]
	s_nop 0
	v_sub_f32_e32 v4, v94, v4
	v_sub_f32_e32 v96, v4, v5
	v_and_b32_e32 v4, 0xffff0000, v233
	v_lshlrev_b32_e32 v5, 16, v234
	v_mov_b32_e32 v94, v3
	v_pk_mul_f32 v[4:5], v[94:95], v[4:5]
	s_nop 0
	v_sub_f32_e32 v4, v96, v4
	v_sub_f32_e32 v5, v4, v5
	s_nop 0
	v_mov_b32_e32 v4, v95
	s_waitcnt lgkmcnt(0)
	ds_read_b128 v[232:235], v167 offset:1008
	v_lshlrev_b32_e32 v96, 16, v242
	v_and_b32_e32 v97, 0xffff0000, v242
	v_pk_mul_f32 v[96:97], v[0:1], v[96:97]
	v_lshlrev_b32_e32 v100, 16, v243
	v_and_b32_e32 v101, 0xffff0000, v243
	v_sub_f32_e32 v12, v12, v96
	v_pk_mul_f32 v[100:101], v[2:3], v[100:101]
	v_sub_f32_e32 v12, v12, v97
	v_lshlrev_b32_e32 v106, 16, v244
	v_and_b32_e32 v107, 0xffff0000, v244
	v_sub_f32_e32 v12, v12, v100
	v_pk_mul_f32 v[102:103], v[4:5], v[106:107]
	v_sub_f32_e32 v12, v12, v101
	v_sub_f32_e32 v12, v12, v102
	v_sub_f32_e32 v97, v12, v103
	s_nop 0
	s_waitcnt lgkmcnt(0)
	ds_read_b128 v[242:245], v167 offset:1152
	v_lshlrev_b32_e32 v12, 16, v232
	v_fma_f32 v96, -v0, v12, v13
	v_and_b32_e32 v12, 0xffff0000, v232
	v_lshlrev_b32_e32 v13, 16, v233
	v_pk_mul_f32 v[12:13], v[86:87], v[12:13]
	s_nop 0
	v_sub_f32_e32 v12, v96, v12
	v_sub_f32_e32 v96, v12, v13
	v_and_b32_e32 v12, 0xffff0000, v233
	v_lshlrev_b32_e32 v13, 16, v234
	v_pk_mul_f32 v[12:13], v[94:95], v[12:13]
	s_nop 0
	v_sub_f32_e32 v12, v96, v12
	v_sub_f32_e32 v100, v12, v13
	v_and_b32_e32 v12, 0xffff0000, v234
	v_lshlrev_b32_e32 v13, 16, v235
	v_mov_b32_e32 v96, v5
	v_pk_mul_f32 v[12:13], v[96:97], v[12:13]
	s_nop 0
	v_sub_f32_e32 v12, v100, v12
	v_sub_f32_e32 v13, v12, v13
	s_nop 0
	v_mov_b32_e32 v12, v97
	s_waitcnt lgkmcnt(0)
	ds_read_b128 v[232:235], v167 offset:1296
	ds_read_b32 v236, v167 offset:1312
	v_lshlrev_b32_e32 v106, 16, v242
	v_and_b32_e32 v107, 0xffff0000, v242
	v_pk_mul_f32 v[106:107], v[0:1], v[106:107]
	v_lshlrev_b32_e32 v100, 16, v243
	v_and_b32_e32 v101, 0xffff0000, v243
	v_sub_f32_e32 v6, v6, v106
	v_pk_mul_f32 v[100:101], v[2:3], v[100:101]
	v_sub_f32_e32 v6, v6, v107
	v_lshlrev_b32_e32 v110, 16, v244
	v_and_b32_e32 v111, 0xffff0000, v244
	v_sub_f32_e32 v6, v6, v100
	v_pk_mul_f32 v[110:111], v[4:5], v[110:111]
	v_sub_f32_e32 v6, v6, v101
	v_lshlrev_b32_e32 v102, 16, v245
	v_and_b32_e32 v103, 0xffff0000, v245
	v_sub_f32_e32 v6, v6, v110
	v_pk_mul_f32 v[102:103], v[12:13], v[102:103]
	v_sub_f32_e32 v6, v6, v111
	v_sub_f32_e32 v6, v6, v102
	v_sub_f32_e32 v101, v6, v103
	s_nop 0
	s_nop 0
	s_waitcnt lgkmcnt(0)
	ds_read_b128 v[242:245], v167 offset:1440
	ds_read_b32 v246, v167 offset:1456
	v_lshlrev_b32_e32 v6, 16, v232
	v_fma_f32 v102, -v0, v6, v7
	v_and_b32_e32 v6, 0xffff0000, v232
	v_lshlrev_b32_e32 v7, 16, v233
	v_pk_mul_f32 v[6:7], v[86:87], v[6:7]
	s_nop 0
	v_sub_f32_e32 v6, v102, v6
	v_sub_f32_e32 v102, v6, v7
	v_and_b32_e32 v6, 0xffff0000, v233
	v_lshlrev_b32_e32 v7, 16, v234
	v_pk_mul_f32 v[6:7], v[94:95], v[6:7]
	s_nop 0
	v_sub_f32_e32 v6, v102, v6
	v_sub_f32_e32 v102, v6, v7
	v_and_b32_e32 v6, 0xffff0000, v234
	v_lshlrev_b32_e32 v7, 16, v235
	v_pk_mul_f32 v[6:7], v[96:97], v[6:7]
	s_nop 0
	v_sub_f32_e32 v6, v102, v6
	v_sub_f32_e32 v102, v6, v7
	v_and_b32_e32 v6, 0xffff0000, v235
	s_waitcnt lgkmcnt(0)
	v_lshlrev_b32_e32 v7, 16, v236
	v_mov_b32_e32 v100, v13
	v_pk_mul_f32 v[6:7], v[100:101], v[6:7]
	s_nop 0
	v_sub_f32_e32 v6, v102, v6
	v_sub_f32_e32 v7, v6, v7
	s_nop 0
	s_nop 0
	s_waitcnt lgkmcnt(0)
	ds_read_b128 v[232:235], v167 offset:1584
	ds_read_b64 v[236:237], v167 offset:1600
	v_lshlrev_b32_e32 v102, 16, v242
	v_and_b32_e32 v103, 0xffff0000, v242
	v_pk_mul_f32 v[102:103], v[0:1], v[102:103]
	v_lshlrev_b32_e32 v106, 16, v243
	v_and_b32_e32 v107, 0xffff0000, v243
	v_sub_f32_e32 v8, v8, v102
	v_pk_mul_f32 v[106:107], v[2:3], v[106:107]
	v_sub_f32_e32 v8, v8, v103
	v_lshlrev_b32_e32 v110, 16, v244
	v_and_b32_e32 v111, 0xffff0000, v244
	v_sub_f32_e32 v8, v8, v106
	v_pk_mul_f32 v[110:111], v[4:5], v[110:111]
	v_sub_f32_e32 v8, v8, v107
	v_lshlrev_b32_e32 v112, 16, v245
	v_and_b32_e32 v113, 0xffff0000, v245
	v_sub_f32_e32 v8, v8, v110
	v_pk_mul_f32 v[112:113], v[12:13], v[112:113]
	v_sub_f32_e32 v8, v8, v111
	s_waitcnt lgkmcnt(0)
	v_lshlrev_b32_e32 v114, 16, v246
	v_and_b32_e32 v115, 0xffff0000, v246
	v_mov_b32_e32 v6, v101
	v_sub_f32_e32 v8, v8, v112
	v_pk_mul_f32 v[114:115], v[6:7], v[114:115]
	v_sub_f32_e32 v8, v8, v113
	v_sub_f32_e32 v8, v8, v114
	v_sub_f32_e32 v103, v8, v115
	s_nop 0
	s_nop 0
	s_waitcnt lgkmcnt(0)
	ds_read_b128 v[242:245], v167 offset:1728
	ds_read_b64 v[246:247], v167 offset:1744
	v_lshlrev_b32_e32 v8, 16, v232
	v_fma_f32 v102, -v0, v8, v9
	v_and_b32_e32 v8, 0xffff0000, v232
	v_lshlrev_b32_e32 v9, 16, v233
	v_pk_mul_f32 v[8:9], v[86:87], v[8:9]
	s_nop 0
	v_sub_f32_e32 v8, v102, v8
	v_sub_f32_e32 v86, v8, v9
	v_and_b32_e32 v8, 0xffff0000, v233
	v_lshlrev_b32_e32 v9, 16, v234
	v_pk_mul_f32 v[8:9], v[94:95], v[8:9]
	v_mov_b32_e32 v102, v7
	v_sub_f32_e32 v8, v86, v8
	v_sub_f32_e32 v86, v8, v9
	v_and_b32_e32 v8, 0xffff0000, v234
	v_lshlrev_b32_e32 v9, 16, v235
	v_pk_mul_f32 v[8:9], v[96:97], v[8:9]
	s_nop 0
	v_sub_f32_e32 v8, v86, v8
	v_sub_f32_e32 v86, v8, v9
	v_and_b32_e32 v8, 0xffff0000, v235
	s_waitcnt lgkmcnt(0)
	v_lshlrev_b32_e32 v9, 16, v236
	v_pk_mul_f32 v[8:9], v[100:101], v[8:9]
	s_nop 0
	v_sub_f32_e32 v8, v86, v8
	v_sub_f32_e32 v86, v8, v9
	v_and_b32_e32 v8, 0xffff0000, v236
	v_lshlrev_b32_e32 v9, 16, v237
	v_pk_mul_f32 v[8:9], v[102:103], v[8:9]
	s_nop 0
	v_sub_f32_e32 v8, v86, v8
	v_sub_f32_e32 v9, v8, v9
	s_nop 0
	s_nop 0
	s_waitcnt lgkmcnt(0)
	ds_read_b128 v[232:235], v167 offset:1872
	ds_read_b128 v[236:239], v167 offset:1888
	v_lshlrev_b32_e32 v8, 16, v242
	v_and_b32_e32 v86, 0xffff0000, v242
	v_fma_f32 v8, -v0, v8, v10
	v_lshlrev_b32_e32 v110, 16, v243
	v_and_b32_e32 v111, 0xffff0000, v243
	v_fma_f32 v8, -v1, v86, v8
	v_pk_mul_f32 v[110:111], v[2:3], v[110:111]
	s_nop 0
	v_sub_f32_e32 v2, v8, v110
	v_sub_f32_e32 v2, v2, v111
	v_lshlrev_b32_e32 v110, 16, v244
	v_and_b32_e32 v111, 0xffff0000, v244
	v_pk_mul_f32 v[110:111], v[4:5], v[110:111]
	v_mov_b32_e32 v8, v103
	v_sub_f32_e32 v2, v2, v110
	v_sub_f32_e32 v2, v2, v111
	v_lshlrev_b32_e32 v110, 16, v245
	v_and_b32_e32 v111, 0xffff0000, v245
	v_pk_mul_f32 v[110:111], v[12:13], v[110:111]
	s_nop 0
	v_sub_f32_e32 v2, v2, v110
	v_sub_f32_e32 v2, v2, v111
	s_waitcnt lgkmcnt(0)
	v_lshlrev_b32_e32 v110, 16, v246
	v_and_b32_e32 v111, 0xffff0000, v246
	v_pk_mul_f32 v[110:111], v[6:7], v[110:111]
	v_lshlrev_b32_e32 v106, 16, v247
	v_sub_f32_e32 v2, v2, v110
	v_and_b32_e32 v107, 0xffff0000, v247
	v_sub_f32_e32 v2, v2, v111
	v_pk_mul_f32 v[106:107], v[8:9], v[106:107]
	s_nop 0
	v_sub_f32_e32 v2, v2, v106
	v_sub_f32_e32 v107, v2, v107
	s_nop 0
	s_nop 0
	v_mov_b32_e32 v106, v9
	s_waitcnt lgkmcnt(0)
	ds_read_b128 v[242:245], v167 offset:2016
	ds_read_b96 v[246:248], v167 offset:2032
	v_lshlrev_b32_e32 v2, 16, v232
	v_and_b32_e32 v10, 0xffff0000, v232
	v_fma_f32 v2, -v0, v2, v11
	v_lshlrev_b32_e32 v86, 16, v233
	v_fma_f32 v2, -v1, v10, v2
	v_and_b32_e32 v10, 0xffff0000, v233
	v_lshlrev_b32_e32 v11, 16, v234
	v_fma_f32 v2, -v87, v86, v2
	v_pk_mul_f32 v[10:11], v[94:95], v[10:11]
	s_nop 0
	v_sub_f32_e32 v2, v2, v10
	v_sub_f32_e32 v2, v2, v11
	v_and_b32_e32 v10, 0xffff0000, v234
	v_lshlrev_b32_e32 v11, 16, v235
	v_pk_mul_f32 v[10:11], v[96:97], v[10:11]
	s_nop 0
	v_sub_f32_e32 v2, v2, v10
	v_sub_f32_e32 v2, v2, v11
	v_and_b32_e32 v10, 0xffff0000, v235
	s_waitcnt lgkmcnt(0)
	v_lshlrev_b32_e32 v11, 16, v236
	v_pk_mul_f32 v[10:11], v[100:101], v[10:11]
	s_nop 0
	v_sub_f32_e32 v2, v2, v10
	v_sub_f32_e32 v2, v2, v11
	v_and_b32_e32 v10, 0xffff0000, v236
	v_lshlrev_b32_e32 v11, 16, v237
	v_pk_mul_f32 v[10:11], v[102:103], v[10:11]
	s_nop 0
	v_sub_f32_e32 v2, v2, v10
	v_sub_f32_e32 v2, v2, v11
	v_and_b32_e32 v10, 0xffff0000, v237
	v_lshlrev_b32_e32 v11, 16, v238
	v_pk_mul_f32 v[10:11], v[106:107], v[10:11]
	s_nop 0
	v_sub_f32_e32 v2, v2, v10
	v_sub_f32_e32 v11, v2, v11
	s_nop 0
	s_nop 0
	s_waitcnt lgkmcnt(0)
	ds_read_b128 v[232:235], v167 offset:2160
	ds_read_b128 v[236:239], v167 offset:2176
	v_lshlrev_b32_e32 v2, 16, v242
	v_and_b32_e32 v10, 0xffff0000, v242
	v_fma_f32 v2, -v0, v2, v16
	v_lshlrev_b32_e32 v86, 16, v243
	v_fma_f32 v2, -v1, v10, v2
	v_and_b32_e32 v94, 0xffff0000, v243
	v_fma_f32 v2, -v87, v86, v2
	v_lshlrev_b32_e32 v110, 16, v244
	v_and_b32_e32 v111, 0xffff0000, v244
	v_fma_f32 v2, -v3, v94, v2
	v_pk_mul_f32 v[110:111], v[4:5], v[110:111]
	v_mov_b32_e32 v10, v107
	v_sub_f32_e32 v2, v2, v110
	v_sub_f32_e32 v2, v2, v111
	v_lshlrev_b32_e32 v110, 16, v245
	v_and_b32_e32 v111, 0xffff0000, v245
	v_pk_mul_f32 v[110:111], v[12:13], v[110:111]
	s_nop 0
	v_sub_f32_e32 v2, v2, v110
	v_sub_f32_e32 v2, v2, v111
	s_waitcnt lgkmcnt(0)
	v_lshlrev_b32_e32 v110, 16, v246
	v_and_b32_e32 v111, 0xffff0000, v246
	v_pk_mul_f32 v[110:111], v[6:7], v[110:111]
	s_nop 0
	v_sub_f32_e32 v2, v2, v110
	v_sub_f32_e32 v2, v2, v111
	v_lshlrev_b32_e32 v110, 16, v247
	v_and_b32_e32 v111, 0xffff0000, v247
	v_pk_mul_f32 v[110:111], v[8:9], v[110:111]
	s_nop 0
	v_sub_f32_e32 v2, v2, v110
	v_sub_f32_e32 v2, v2, v111
	v_lshlrev_b32_e32 v110, 16, v248
	v_and_b32_e32 v111, 0xffff0000, v248
	v_pk_mul_f32 v[110:111], v[10:11], v[110:111]
	s_nop 0
	v_sub_f32_e32 v2, v2, v110
	v_sub_f32_e32 v111, v2, v111
	s_nop 0
	s_nop 0
	v_mov_b32_e32 v110, v11
	s_waitcnt lgkmcnt(0)
	ds_read_b32 v242, v167 offset:2480
	v_lshlrev_b32_e32 v2, 16, v232
	v_and_b32_e32 v4, 0xffff0000, v232
	v_fma_f32 v2, -v0, v2, v17
	v_lshlrev_b32_e32 v6, 16, v233
	v_fma_f32 v2, -v1, v4, v2
	v_and_b32_e32 v8, 0xffff0000, v233
	v_fma_f32 v2, -v87, v6, v2
	v_lshlrev_b32_e32 v10, 16, v234
	v_fma_f32 v2, -v3, v8, v2
	v_and_b32_e32 v16, 0xffff0000, v234
	v_lshlrev_b32_e32 v17, 16, v235
	v_fma_f32 v2, -v95, v10, v2
	v_pk_mul_f32 v[16:17], v[96:97], v[16:17]
	v_cvt_pk_bf16_f32 v112, v0, v1
	v_cvt_pk_bf16_f32 v113, v87, v3
	v_cvt_pk_bf16_f32 v114, v95, v5
	v_add_u32_e32 v6, 0x400, v189
	v_sub_f32_e32 v2, v2, v16
	v_sub_f32_e32 v2, v2, v17
	v_and_b32_e32 v16, 0xffff0000, v235
	s_waitcnt lgkmcnt(0)
	v_lshlrev_b32_e32 v17, 16, v236
	v_pk_mul_f32 v[16:17], v[100:101], v[16:17]
	v_cvt_pk_bf16_f32 v115, v97, v13
	v_add_u32_e32 v8, 0x800, v189
	v_sub_f32_e32 v2, v2, v16
	v_sub_f32_e32 v2, v2, v17
	v_and_b32_e32 v16, 0xffff0000, v236
	v_lshlrev_b32_e32 v17, 16, v237
	v_pk_mul_f32 v[16:17], v[102:103], v[16:17]
	v_add_u32_e32 v10, 0xc00, v189
	v_sub_f32_e32 v2, v2, v16
	v_sub_f32_e32 v2, v2, v17
	v_and_b32_e32 v16, 0xffff0000, v237
	v_lshlrev_b32_e32 v17, 16, v238
	v_pk_mul_f32 v[16:17], v[106:107], v[16:17]
	s_nop 0
	v_sub_f32_e32 v2, v2, v16
	v_sub_f32_e32 v2, v2, v17
	v_and_b32_e32 v16, 0xffff0000, v238
	v_lshlrev_b32_e32 v17, 16, v239
	v_pk_mul_f32 v[16:17], v[110:111], v[16:17]
	s_nop 0
	v_sub_f32_e32 v2, v2, v16
	v_sub_f32_e32 v2, v2, v17
	ds_write_b128 v186, v[112:115]
	v_cvt_pk_bf16_f32 v112, v101, v7
	v_cvt_pk_bf16_f32 v113, v103, v9
	v_cvt_pk_bf16_f32 v114, v107, v11
	v_cvt_pk_bf16_f32 v115, v111, v2
	ds_write_b128 v186, v[112:115] offset:16
	s_waitcnt lgkmcnt(0)
	ds_read_b128 v[112:115], v187
	ds_read_b128 v[116:119], v188
	ds_read_b128 v[120:123], v188 offset:2304
	ds_read_b128 v[124:127], v188 offset:4608
	ds_read_b128 v[128:131], v188 offset:6912
	s_waitcnt lgkmcnt(0)
	v_cndmask_b32_e64 v115, 0, v115, s[52:53]
	v_cndmask_b32_e64 v114, 0, v114, s[52:53]
	v_cndmask_b32_e64 v113, 0, v113, s[52:53]
	v_cndmask_b32_e64 v112, 0, v112, s[52:53]
	s_waitcnt lgkmcnt(3)
	s_nop 0
	v_mfma_f32_16x16x32_bf16 v[116:119], v[112:115], v[116:119], 0
	s_waitcnt lgkmcnt(2)
	v_mfma_f32_16x16x32_bf16 v[120:123], v[112:115], v[120:123], 0
	s_waitcnt lgkmcnt(1)
	v_mfma_f32_16x16x32_bf16 v[124:127], v[112:115], v[124:127], 0
	s_waitcnt lgkmcnt(0)
	v_mfma_f32_16x16x32_bf16 v[112:115], v[112:115], v[128:131], 0
	s_nop 3
	ds_write2_b32 v189, v116, v120 offset1:16
	ds_write2_b32 v6, v117, v121 offset1:16
	ds_write2_b32 v8, v118, v122 offset1:16
	ds_write2_b32 v10, v119, v123 offset1:16
	ds_write2_b32 v189, v124, v112 offset0:32 offset1:48
	ds_write2_b32 v6, v125, v113 offset0:32 offset1:48
	ds_write2_b32 v8, v126, v114 offset0:32 offset1:48
	ds_write2_b32 v10, v127, v115 offset0:32 offset1:48
	s_waitcnt lgkmcnt(0)
	ds_read2st64_b32 v[16:17], v178 offset1:4
	ds_read2st64_b32 v[112:113], v178 offset0:8 offset1:12
	ds_read2st64_b32 v[114:115], v178 offset0:16 offset1:20
	ds_read2st64_b32 v[116:117], v178 offset0:24 offset1:28
	s_waitcnt lgkmcnt(0)
	v_sub_f32_e32 v4, v15, v17
	s_waitcnt lgkmcnt(2)
	v_sub_f32_e32 v12, v18, v112
	v_sub_f32_e32 v86, v19, v113
	ds_read2st64_b32 v[18:19], v178 offset0:32 offset1:36
	s_waitcnt lgkmcnt(2)
	v_sub_f32_e32 v94, v20, v114
	v_sub_f32_e32 v96, v21, v115
	v_pk_mov_b32 v[14:15], v[24:25], v[14:15] op_sel:[1,0]
	s_waitcnt lgkmcnt(1)
	v_mov_b32_e32 v20, v117
	v_mov_b32_e32 v21, v16
	s_waitcnt lgkmcnt(0)
	v_sub_f32_e32 v102, v26, v18
	v_sub_f32_e32 v106, v27, v19
	ds_read2st64_b32 v[18:19], v178 offset0:56 offset1:60
	v_pk_add_f32 v[20:21], v[14:15], v[20:21] neg_lo:[0,1] neg_hi:[0,1]
	ds_read2st64_b32 v[14:15], v178 offset0:40 offset1:44
	ds_read2st64_b32 v[16:17], v178 offset0:48 offset1:52
	v_sub_f32_e32 v100, v24, v116
	s_waitcnt lgkmcnt(0)
	v_sub_f32_e32 v129, v76, v18
	v_sub_f32_e32 v132, v77, v19
	s_waitcnt lgkmcnt(1)
	v_sub_f32_e32 v110, v30, v14
	v_sub_f32_e32 v122, v31, v15
	s_waitcnt lgkmcnt(0)
	v_sub_f32_e32 v124, v66, v16
	v_sub_f32_e32 v128, v67, v17
	s_nop 0
	s_waitcnt lgkmcnt(0)
	ds_read_b32 v232, v167 offset:2624
	v_lshlrev_b32_e32 v14, 16, v242
	v_fma_f32 v15, -v21, v14, v4
	s_nop 0
	v_mov_b32_e32 v14, v21
	s_waitcnt lgkmcnt(0)
	ds_read_b128 v[242:245], v167 offset:2768
	v_lshlrev_b32_e32 v16, 16, v232
	v_and_b32_e32 v17, 0xffff0000, v232
	v_pk_mul_f32 v[16:17], v[14:15], v[16:17]
	s_nop 0
	v_sub_f32_e32 v4, v12, v16
	v_sub_f32_e32 v17, v4, v17
	s_nop 0
	v_mov_b32_e32 v16, v15
	s_waitcnt lgkmcnt(0)
	ds_read_b64 v[232:233], v167 offset:2912
	v_lshlrev_b32_e32 v4, 16, v242
	v_and_b32_e32 v18, 0xffff0000, v242
	v_lshlrev_b32_e32 v19, 16, v243
	v_fma_f32 v4, -v21, v4, v86
	v_pk_mul_f32 v[18:19], v[16:17], v[18:19]
	s_nop 0
	v_sub_f32_e32 v4, v4, v18
	v_sub_f32_e32 v19, v4, v19
	s_nop 0
	v_mov_b32_e32 v18, v17
	s_waitcnt lgkmcnt(0)
	ds_read_b128 v[242:245], v167 offset:3056
	v_lshlrev_b32_e32 v26, 16, v232
	v_and_b32_e32 v27, 0xffff0000, v232
	v_pk_mul_f32 v[26:27], v[14:15], v[26:27]
	v_lshlrev_b32_e32 v24, 16, v233
	v_and_b32_e32 v25, 0xffff0000, v233
	v_sub_f32_e32 v4, v94, v26
	v_pk_mul_f32 v[24:25], v[18:19], v[24:25]
	v_sub_f32_e32 v4, v4, v27
	v_sub_f32_e32 v4, v4, v24
	v_sub_f32_e32 v25, v4, v25
	s_nop 0
	v_mov_b32_e32 v24, v19
	s_waitcnt lgkmcnt(0)
	ds_read_b96 v[232:234], v167 offset:3200
	v_lshlrev_b32_e32 v4, 16, v242
	v_and_b32_e32 v26, 0xffff0000, v242
	v_lshlrev_b32_e32 v27, 16, v243
	v_fma_f32 v4, -v21, v4, v96
	v_pk_mul_f32 v[26:27], v[16:17], v[26:27]
	v_and_b32_e32 v30, 0xffff0000, v243
	v_lshlrev_b32_e32 v31, 16, v244
	v_sub_f32_e32 v4, v4, v26
	v_sub_f32_e32 v4, v4, v27
	v_pk_mul_f32 v[26:27], v[24:25], v[30:31]
	s_nop 0
	v_sub_f32_e32 v4, v4, v26
	v_sub_f32_e32 v27, v4, v27
	s_nop 0
	v_mov_b32_e32 v26, v25
	s_waitcnt lgkmcnt(0)
	ds_read_b128 v[242:245], v167 offset:3344
	v_lshlrev_b32_e32 v30, 16, v232
	v_and_b32_e32 v31, 0xffff0000, v232
	v_pk_mul_f32 v[30:31], v[14:15], v[30:31]
	s_nop 0
	v_sub_f32_e32 v4, v100, v30
	v_sub_f32_e32 v4, v4, v31
	v_lshlrev_b32_e32 v30, 16, v233
	v_and_b32_e32 v31, 0xffff0000, v233
	v_pk_mul_f32 v[30:31], v[18:19], v[30:31]
	s_nop 0
	v_sub_f32_e32 v4, v4, v30
	v_sub_f32_e32 v4, v4, v31
	v_lshlrev_b32_e32 v30, 16, v234
	v_and_b32_e32 v31, 0xffff0000, v234
	v_pk_mul_f32 v[30:31], v[26:27], v[30:31]
	s_nop 0
	v_sub_f32_e32 v4, v4, v30
	v_sub_f32_e32 v31, v4, v31
	s_nop 0
	v_mov_b32_e32 v30, v27
	s_waitcnt lgkmcnt(0)
	ds_read_b128 v[232:235], v167 offset:3488
	v_lshlrev_b32_e32 v4, 16, v242
	v_and_b32_e32 v66, 0xffff0000, v242
	v_lshlrev_b32_e32 v67, 16, v243
	v_fma_f32 v4, -v21, v4, v20
	v_pk_mul_f32 v[66:67], v[16:17], v[66:67]
	s_nop 0
	v_sub_f32_e32 v4, v4, v66
	v_sub_f32_e32 v4, v4, v67
	v_and_b32_e32 v66, 0xffff0000, v243
	v_lshlrev_b32_e32 v67, 16, v244
	v_pk_mul_f32 v[66:67], v[24:25], v[66:67]
	s_nop 0
	v_sub_f32_e32 v4, v4, v66
	v_sub_f32_e32 v4, v4, v67
	v_and_b32_e32 v66, 0xffff0000, v244
	v_lshlrev_b32_e32 v67, 16, v245
	v_pk_mul_f32 v[66:67], v[30:31], v[66:67]
	s_nop 0
	v_sub_f32_e32 v4, v4, v66
	v_sub_f32_e32 v67, v4, v67
	s_nop 0
	v_mov_b32_e32 v66, v31
	s_waitcnt lgkmcnt(0)
	ds_read_b128 v[242:245], v167 offset:3632
	ds_read_b32 v246, v167 offset:3648
	v_lshlrev_b32_e32 v76, 16, v232
	v_and_b32_e32 v77, 0xffff0000, v232
	v_pk_mul_f32 v[76:77], v[14:15], v[76:77]
	s_nop 0
	v_sub_f32_e32 v4, v102, v76
	v_sub_f32_e32 v4, v4, v77
	v_lshlrev_b32_e32 v76, 16, v233
	v_and_b32_e32 v77, 0xffff0000, v233
	v_pk_mul_f32 v[76:77], v[18:19], v[76:77]
	s_nop 0
	v_sub_f32_e32 v4, v4, v76
	v_sub_f32_e32 v4, v4, v77
	v_lshlrev_b32_e32 v76, 16, v234
	v_and_b32_e32 v77, 0xffff0000, v234
	v_pk_mul_f32 v[76:77], v[26:27], v[76:77]
	s_nop 0
	v_sub_f32_e32 v4, v4, v76
	v_sub_f32_e32 v4, v4, v77
	v_lshlrev_b32_e32 v76, 16, v235
	v_and_b32_e32 v77, 0xffff0000, v235
	v_pk_mul_f32 v[76:77], v[66:67], v[76:77]
	s_nop 0
	v_sub_f32_e32 v4, v4, v76
	v_sub_f32_e32 v77, v4, v77
	s_nop 0
	s_nop 0
	v_mov_b32_e32 v76, v67
	s_waitcnt lgkmcnt(0)
	ds_read_b128 v[232:235], v167 offset:3776
	ds_read_b32 v236, v167 offset:3792
	v_lshlrev_b32_e32 v12, 16, v242
	v_and_b32_e32 v116, 0xffff0000, v242
	v_lshlrev_b32_e32 v117, 16, v243
	v_fma_f32 v12, -v21, v12, v106
	v_pk_mul_f32 v[116:117], v[16:17], v[116:117]
	v_and_b32_e32 v112, 0xffff0000, v243
	v_sub_f32_e32 v12, v12, v116
	v_lshlrev_b32_e32 v113, 16, v244
	v_sub_f32_e32 v12, v12, v117
	v_pk_mul_f32 v[112:113], v[24:25], v[112:113]
	s_nop 0
	v_sub_f32_e32 v12, v12, v112
	v_sub_f32_e32 v12, v12, v113
	v_and_b32_e32 v112, 0xffff0000, v244
	v_lshlrev_b32_e32 v113, 16, v245
	v_pk_mul_f32 v[112:113], v[30:31], v[112:113]
	s_nop 0
	v_sub_f32_e32 v12, v12, v112
	v_sub_f32_e32 v12, v12, v113
	v_and_b32_e32 v112, 0xffff0000, v245
	s_waitcnt lgkmcnt(0)
	v_lshlrev_b32_e32 v113, 16, v246
	v_pk_mul_f32 v[112:113], v[76:77], v[112:113]
	s_nop 0
	v_sub_f32_e32 v4, v12, v112
	v_sub_f32_e32 v113, v4, v113
	s_nop 0
	s_nop 0
	v_mov_b32_e32 v112, v77
	s_waitcnt lgkmcnt(0)
	ds_read_b128 v[242:245], v167 offset:3920
	ds_read_b64 v[246:247], v167 offset:3936
	v_lshlrev_b32_e32 v118, 16, v232
	v_and_b32_e32 v119, 0xffff0000, v232
	v_pk_mul_f32 v[118:119], v[14:15], v[118:119]
	v_lshlrev_b32_e32 v114, 16, v233
	v_sub_f32_e32 v12, v110, v118
	v_and_b32_e32 v115, 0xffff0000, v233
	v_sub_f32_e32 v12, v12, v119
	v_pk_mul_f32 v[114:115], v[18:19], v[114:115]
	s_nop 0
	v_sub_f32_e32 v12, v12, v114
	v_sub_f32_e32 v12, v12, v115
	v_lshlrev_b32_e32 v114, 16, v234
	v_and_b32_e32 v115, 0xffff0000, v234
	v_pk_mul_f32 v[114:115], v[26:27], v[114:115]
	s_nop 0
	v_sub_f32_e32 v12, v12, v114
	v_sub_f32_e32 v12, v12, v115
	v_lshlrev_b32_e32 v114, 16, v235
	v_and_b32_e32 v115, 0xffff0000, v235
	v_pk_mul_f32 v[114:115], v[66:67], v[114:115]
	s_nop 0
	v_sub_f32_e32 v12, v12, v114
	v_sub_f32_e32 v12, v12, v115
	s_waitcnt lgkmcnt(0)
	v_lshlrev_b32_e32 v114, 16, v236
	v_and_b32_e32 v115, 0xffff0000, v236
	v_pk_mul_f32 v[114:115], v[112:113], v[114:115]
	s_nop 0
	v_sub_f32_e32 v4, v12, v114
	v_sub_f32_e32 v115, v4, v115
	s_nop 0
	s_nop 0
	v_mov_b32_e32 v114, v113
	s_waitcnt lgkmcnt(0)
	ds_read_b128 v[232:235], v167 offset:4064
	ds_read_b64 v[236:237], v167 offset:4080
	v_lshlrev_b32_e32 v4, 16, v242
	v_fma_f32 v4, -v21, v4, v122
	v_and_b32_e32 v122, 0xffff0000, v242
	v_lshlrev_b32_e32 v123, 16, v243
	v_pk_mul_f32 v[122:123], v[16:17], v[122:123]
	v_and_b32_e32 v116, 0xffff0000, v243
	v_sub_f32_e32 v4, v4, v122
	v_lshlrev_b32_e32 v117, 16, v244
	v_sub_f32_e32 v4, v4, v123
	v_pk_mul_f32 v[116:117], v[24:25], v[116:117]
	s_nop 0
	v_sub_f32_e32 v4, v4, v116
	v_sub_f32_e32 v4, v4, v117
	v_and_b32_e32 v116, 0xffff0000, v244
	v_lshlrev_b32_e32 v117, 16, v245
	v_pk_mul_f32 v[116:117], v[30:31], v[116:117]
	s_nop 0
	v_sub_f32_e32 v4, v4, v116
	v_sub_f32_e32 v4, v4, v117
	v_and_b32_e32 v116, 0xffff0000, v245
	s_waitcnt lgkmcnt(0)
	v_lshlrev_b32_e32 v117, 16, v246
	v_pk_mul_f32 v[116:117], v[76:77], v[116:117]
	s_nop 0
	v_sub_f32_e32 v4, v4, v116
	v_sub_f32_e32 v4, v4, v117
	v_and_b32_e32 v116, 0xffff0000, v246
	v_lshlrev_b32_e32 v117, 16, v247
	v_pk_mul_f32 v[116:117], v[114:115], v[116:117]
	s_nop 0
	v_sub_f32_e32 v4, v4, v116
	v_sub_f32_e32 v117, v4, v117
	s_nop 0
	s_nop 0
	v_mov_b32_e32 v116, v115
	s_waitcnt lgkmcnt(0)
	ds_read_b128 v[242:245], v167 offset:4208
	ds_read_b128 v[246:249], v167 offset:4224
	v_lshlrev_b32_e32 v4, 16, v232
	v_and_b32_e32 v12, 0xffff0000, v232
	v_fma_f32 v4, -v21, v4, v124
	v_lshlrev_b32_e32 v118, 16, v233
	v_and_b32_e32 v119, 0xffff0000, v233
	v_fma_f32 v4, -v15, v12, v4
	v_pk_mul_f32 v[118:119], v[18:19], v[118:119]
	s_nop 0
	v_sub_f32_e32 v4, v4, v118
	v_sub_f32_e32 v4, v4, v119
	v_lshlrev_b32_e32 v118, 16, v234
	v_and_b32_e32 v119, 0xffff0000, v234
	v_pk_mul_f32 v[118:119], v[26:27], v[118:119]
	s_nop 0
	v_sub_f32_e32 v4, v4, v118
	v_sub_f32_e32 v4, v4, v119
	v_lshlrev_b32_e32 v118, 16, v235
	v_and_b32_e32 v119, 0xffff0000, v235
	v_pk_mul_f32 v[118:119], v[66:67], v[118:119]
	s_nop 0
	v_sub_f32_e32 v4, v4, v118
	v_sub_f32_e32 v4, v4, v119
	s_waitcnt lgkmcnt(0)
	v_lshlrev_b32_e32 v118, 16, v236
	v_and_b32_e32 v119, 0xffff0000, v236
	v_pk_mul_f32 v[118:119], v[112:113], v[118:119]
	s_nop 0
	v_sub_f32_e32 v4, v4, v118
	v_sub_f32_e32 v4, v4, v119
	v_lshlrev_b32_e32 v118, 16, v237
	v_and_b32_e32 v119, 0xffff0000, v237
	v_pk_mul_f32 v[118:119], v[116:117], v[118:119]
	s_nop 0
	v_sub_f32_e32 v4, v4, v118
	v_sub_f32_e32 v119, v4, v119
	s_nop 0
	s_nop 0
	v_mov_b32_e32 v118, v117
	s_waitcnt lgkmcnt(0)
	ds_read_b128 v[232:235], v167 offset:4352
	ds_read_b96 v[236:238], v167 offset:4368
	v_lshlrev_b32_e32 v4, 16, v242
	v_and_b32_e32 v12, 0xffff0000, v242
	v_fma_f32 v4, -v21, v4, v128
	v_lshlrev_b32_e32 v14, 16, v243
	v_fma_f32 v4, -v15, v12, v4
	v_and_b32_e32 v120, 0xffff0000, v243
	v_lshlrev_b32_e32 v121, 16, v244
	v_fma_f32 v4, -v17, v14, v4
	v_pk_mul_f32 v[120:121], v[24:25], v[120:121]
	s_nop 0
	v_sub_f32_e32 v4, v4, v120
	v_sub_f32_e32 v4, v4, v121
	v_and_b32_e32 v120, 0xffff0000, v244
	v_lshlrev_b32_e32 v121, 16, v245
	v_pk_mul_f32 v[120:121], v[30:31], v[120:121]
	s_nop 0
	v_sub_f32_e32 v4, v4, v120
	v_sub_f32_e32 v4, v4, v121
	v_and_b32_e32 v120, 0xffff0000, v245
	s_waitcnt lgkmcnt(0)
	v_lshlrev_b32_e32 v121, 16, v246
	v_pk_mul_f32 v[120:121], v[76:77], v[120:121]
	s_nop 0
	v_sub_f32_e32 v4, v4, v120
	v_sub_f32_e32 v4, v4, v121
	v_and_b32_e32 v120, 0xffff0000, v246
	v_lshlrev_b32_e32 v121, 16, v247
	v_pk_mul_f32 v[120:121], v[114:115], v[120:121]
	s_nop 0
	v_sub_f32_e32 v4, v4, v120
	v_sub_f32_e32 v4, v4, v121
	v_and_b32_e32 v120, 0xffff0000, v247
	v_lshlrev_b32_e32 v121, 16, v248
	v_pk_mul_f32 v[120:121], v[118:119], v[120:121]
	s_nop 0
	v_sub_f32_e32 v4, v4, v120
	v_sub_f32_e32 v121, v4, v121
	s_nop 0
	s_nop 0
	v_mov_b32_e32 v120, v119
	s_waitcnt lgkmcnt(0)
	ds_read_b128 v[242:245], v167 offset:4496
	ds_read_b128 v[246:249], v167 offset:4512
	v_lshlrev_b32_e32 v4, 16, v232
	v_and_b32_e32 v12, 0xffff0000, v232
	v_fma_f32 v4, -v21, v4, v129
	v_lshlrev_b32_e32 v14, 16, v233
	v_fma_f32 v4, -v15, v12, v4
	v_and_b32_e32 v16, 0xffff0000, v233
	v_fma_f32 v4, -v17, v14, v4
	v_lshlrev_b32_e32 v122, 16, v234
	v_and_b32_e32 v123, 0xffff0000, v234
	v_fma_f32 v4, -v19, v16, v4
	v_pk_mul_f32 v[122:123], v[26:27], v[122:123]
	s_nop 0
	v_sub_f32_e32 v4, v4, v122
	v_sub_f32_e32 v4, v4, v123
	v_lshlrev_b32_e32 v122, 16, v235
	v_and_b32_e32 v123, 0xffff0000, v235
	v_pk_mul_f32 v[122:123], v[66:67], v[122:123]
	s_nop 0
	v_sub_f32_e32 v4, v4, v122
	v_sub_f32_e32 v4, v4, v123
	s_waitcnt lgkmcnt(0)
	v_lshlrev_b32_e32 v122, 16, v236
	v_and_b32_e32 v123, 0xffff0000, v236
	v_pk_mul_f32 v[122:123], v[112:113], v[122:123]
	s_nop 0
	v_sub_f32_e32 v4, v4, v122
	v_sub_f32_e32 v4, v4, v123
	v_lshlrev_b32_e32 v122, 16, v237
	v_and_b32_e32 v123, 0xffff0000, v237
	v_pk_mul_f32 v[122:123], v[116:117], v[122:123]
	s_nop 0
	v_sub_f32_e32 v4, v4, v122
	v_sub_f32_e32 v4, v4, v123
	v_lshlrev_b32_e32 v122, 16, v238
	v_and_b32_e32 v123, 0xffff0000, v238
	v_pk_mul_f32 v[122:123], v[120:121], v[122:123]
	s_nop 0
	v_sub_f32_e32 v4, v4, v122
	v_sub_f32_e32 v123, v4, v123
	s_nop 0
	s_nop 0
	v_mov_b32_e32 v122, v121
	s_waitcnt lgkmcnt(0)
	ds_read_b32 v232, v167 offset:4816
	v_lshlrev_b32_e32 v4, 16, v242
	v_and_b32_e32 v12, 0xffff0000, v242
	v_fma_f32 v4, -v21, v4, v132
	v_lshlrev_b32_e32 v14, 16, v243
	v_fma_f32 v4, -v15, v12, v4
	v_and_b32_e32 v16, 0xffff0000, v243
	v_fma_f32 v4, -v17, v14, v4
	v_lshlrev_b32_e32 v18, 16, v244
	v_fma_f32 v4, -v19, v16, v4
	v_and_b32_e32 v124, 0xffff0000, v244
	v_lshlrev_b32_e32 v125, 16, v245
	v_fma_f32 v4, -v25, v18, v4
	v_pk_mul_f32 v[124:125], v[30:31], v[124:125]
	v_cvt_pk_bf16_f32 v126, v25, v27
	s_nop 0
	v_sub_f32_e32 v4, v4, v124
	v_sub_f32_e32 v4, v4, v125
	v_and_b32_e32 v124, 0xffff0000, v245
	s_waitcnt lgkmcnt(0)
	v_lshlrev_b32_e32 v125, 16, v246
	v_pk_mul_f32 v[124:125], v[76:77], v[124:125]
	v_cvt_pk_bf16_f32 v127, v31, v67
	s_nop 0
	v_sub_f32_e32 v4, v4, v124
	v_sub_f32_e32 v4, v4, v125
	v_and_b32_e32 v124, 0xffff0000, v246
	v_lshlrev_b32_e32 v125, 16, v247
	v_pk_mul_f32 v[124:125], v[114:115], v[124:125]
	s_nop 0
	v_sub_f32_e32 v4, v4, v124
	v_sub_f32_e32 v4, v4, v125
	v_and_b32_e32 v124, 0xffff0000, v247
	v_lshlrev_b32_e32 v125, 16, v248
	v_pk_mul_f32 v[124:125], v[118:119], v[124:125]
	s_nop 0
	v_sub_f32_e32 v4, v4, v124
	v_sub_f32_e32 v4, v4, v125
	v_and_b32_e32 v124, 0xffff0000, v248
	v_lshlrev_b32_e32 v125, 16, v249
	v_pk_mul_f32 v[124:125], v[122:123], v[124:125]
	s_nop 0
	v_sub_f32_e32 v4, v4, v124
	v_sub_f32_e32 v4, v4, v125
	v_cvt_pk_bf16_f32 v124, v21, v15
	v_cvt_pk_bf16_f32 v125, v17, v19
	ds_write_b128 v186, v[124:127] offset:32
	v_cvt_pk_bf16_f32 v124, v77, v113
	v_cvt_pk_bf16_f32 v125, v115, v117
	v_cvt_pk_bf16_f32 v126, v119, v121
	v_cvt_pk_bf16_f32 v127, v123, v4
	ds_write_b128 v186, v[124:127] offset:48
	s_waitcnt lgkmcnt(0)
	ds_read_b128 v[124:127], v187 offset:2304
	ds_read_b128 v[128:131], v188
	ds_read_b128 v[132:135], v188 offset:2304
	ds_read_b128 v[192:195], v188 offset:4608
	ds_read_b128 v[212:215], v188 offset:6912
	s_waitcnt lgkmcnt(0)
	v_mfma_f32_16x16x32_bf16 v[128:131], v[124:127], v[128:131], 0
	s_waitcnt lgkmcnt(2)
	v_mfma_f32_16x16x32_bf16 v[132:135], v[124:127], v[132:135], 0
	s_waitcnt lgkmcnt(1)
	v_mfma_f32_16x16x32_bf16 v[192:195], v[124:127], v[192:195], 0
	s_waitcnt lgkmcnt(0)
	v_mfma_f32_16x16x32_bf16 v[124:127], v[124:127], v[212:215], 0
	s_nop 3
	ds_write2_b32 v189, v128, v132 offset1:16
	ds_write2_b32 v6, v129, v133 offset1:16
	ds_write2_b32 v8, v130, v134 offset1:16
	ds_write2_b32 v10, v131, v135 offset1:16
	ds_write2_b32 v189, v192, v124 offset0:32 offset1:48
	ds_write2_b32 v6, v193, v125 offset0:32 offset1:48
	ds_write2_b32 v8, v194, v126 offset0:32 offset1:48
	ds_write2_b32 v10, v195, v127 offset0:32 offset1:48
	s_waitcnt lgkmcnt(0)
	ds_read2st64_b32 v[124:125], v178 offset1:4
	ds_read2st64_b32 v[126:127], v178 offset0:8 offset1:12
	ds_read2st64_b32 v[128:129], v178 offset0:16 offset1:20
	ds_read2st64_b32 v[130:131], v178 offset0:24 offset1:28
	s_waitcnt lgkmcnt(0)
	v_sub_f32_e32 v16, v23, v125
	s_waitcnt lgkmcnt(2)
	v_sub_f32_e32 v18, v28, v126
	v_sub_f32_e32 v20, v29, v127
	ds_read2st64_b32 v[28:29], v178 offset0:32 offset1:36
	s_waitcnt lgkmcnt(2)
	v_sub_f32_e32 v24, v62, v128
	v_sub_f32_e32 v26, v63, v129
	v_pk_mov_b32 v[22:23], v[72:73], v[22:23] op_sel:[1,0]
	s_waitcnt lgkmcnt(1)
	v_mov_b32_e32 v62, v131
	v_mov_b32_e32 v63, v124
	s_waitcnt lgkmcnt(0)
	v_sub_f32_e32 v66, v74, v28
	v_sub_f32_e32 v76, v75, v29
	ds_read2st64_b32 v[28:29], v178 offset0:56 offset1:60
	v_sub_f32_e32 v30, v72, v130
	v_pk_add_f32 v[62:63], v[22:23], v[62:63] neg_lo:[0,1] neg_hi:[0,1]
	ds_read2st64_b32 v[22:23], v178 offset0:40 offset1:44
	ds_read2st64_b32 v[72:73], v178 offset0:48 offset1:52
	s_waitcnt lgkmcnt(0)
	v_sub_f32_e32 v14, v104, v28
	v_sub_f32_e32 v12, v105, v29
	s_waitcnt lgkmcnt(1)
	v_sub_f32_e32 v94, v78, v22
	v_sub_f32_e32 v96, v79, v23
	s_waitcnt lgkmcnt(0)
	v_sub_f32_e32 v100, v84, v72
	v_sub_f32_e32 v102, v85, v73
	s_nop 0
	s_waitcnt lgkmcnt(0)
	ds_read_b32 v242, v167 offset:4960
	v_lshlrev_b32_e32 v22, 16, v232
	v_fma_f32 v23, -v63, v22, v16
	s_nop 0
	v_mov_b32_e32 v22, v63
	s_waitcnt lgkmcnt(0)
	ds_read_b128 v[232:235], v167 offset:5104
	v_lshlrev_b32_e32 v28, 16, v242
	v_and_b32_e32 v29, 0xffff0000, v242
	v_pk_mul_f32 v[28:29], v[22:23], v[28:29]
	s_nop 0
	v_sub_f32_e32 v16, v18, v28
	v_sub_f32_e32 v29, v16, v29
	s_nop 0
	v_mov_b32_e32 v28, v23
	s_waitcnt lgkmcnt(0)
	ds_read_b64 v[242:243], v167 offset:5248
	v_lshlrev_b32_e32 v16, 16, v232
	v_and_b32_e32 v72, 0xffff0000, v232
	v_lshlrev_b32_e32 v73, 16, v233
	v_fma_f32 v16, -v63, v16, v20
	v_pk_mul_f32 v[72:73], v[28:29], v[72:73]
	s_nop 0
	v_sub_f32_e32 v16, v16, v72
	v_sub_f32_e32 v73, v16, v73
	s_nop 0
	v_mov_b32_e32 v72, v29
	s_waitcnt lgkmcnt(0)
	ds_read_b128 v[232:235], v167 offset:5392
	v_lshlrev_b32_e32 v78, 16, v242
	v_and_b32_e32 v79, 0xffff0000, v242
	v_pk_mul_f32 v[78:79], v[22:23], v[78:79]
	v_lshlrev_b32_e32 v74, 16, v243
	v_sub_f32_e32 v16, v24, v78
	v_and_b32_e32 v75, 0xffff0000, v243
	v_sub_f32_e32 v16, v16, v79
	v_pk_mul_f32 v[74:75], v[72:73], v[74:75]
	s_nop 0
	v_sub_f32_e32 v16, v16, v74
	v_sub_f32_e32 v75, v16, v75
	s_nop 0
	v_mov_b32_e32 v74, v73
	s_waitcnt lgkmcnt(0)
	ds_read_b96 v[242:244], v167 offset:5536
	v_lshlrev_b32_e32 v16, 16, v232
	v_and_b32_e32 v78, 0xffff0000, v232
	v_lshlrev_b32_e32 v79, 16, v233
	v_fma_f32 v16, -v63, v16, v26
	v_pk_mul_f32 v[78:79], v[28:29], v[78:79]
	s_nop 0
	v_sub_f32_e32 v16, v16, v78
	v_sub_f32_e32 v16, v16, v79
	v_and_b32_e32 v78, 0xffff0000, v233
	v_lshlrev_b32_e32 v79, 16, v234
	v_pk_mul_f32 v[78:79], v[74:75], v[78:79]
	s_nop 0
	v_sub_f32_e32 v16, v16, v78
	v_sub_f32_e32 v79, v16, v79
	s_nop 0
	v_mov_b32_e32 v78, v75
	s_waitcnt lgkmcnt(0)
	ds_read_b128 v[232:235], v167 offset:5680
	v_lshlrev_b32_e32 v104, 16, v242
	v_and_b32_e32 v105, 0xffff0000, v242
	v_pk_mul_f32 v[104:105], v[22:23], v[104:105]
	v_lshlrev_b32_e32 v84, 16, v243
	v_sub_f32_e32 v16, v30, v104
	v_and_b32_e32 v85, 0xffff0000, v243
	v_sub_f32_e32 v16, v16, v105
	v_pk_mul_f32 v[84:85], v[72:73], v[84:85]
	s_nop 0
	v_sub_f32_e32 v16, v16, v84
	v_sub_f32_e32 v16, v16, v85
	v_lshlrev_b32_e32 v84, 16, v244
	v_and_b32_e32 v85, 0xffff0000, v244
	v_pk_mul_f32 v[84:85], v[78:79], v[84:85]
	s_nop 0
	v_sub_f32_e32 v16, v16, v84
	v_sub_f32_e32 v85, v16, v85
	s_nop 0
	v_mov_b32_e32 v84, v79
	s_waitcnt lgkmcnt(0)
	ds_read_b128 v[242:245], v167 offset:5824
	v_lshlrev_b32_e32 v16, 16, v232
	v_and_b32_e32 v104, 0xffff0000, v232
	v_lshlrev_b32_e32 v105, 16, v233
	v_fma_f32 v16, -v63, v16, v62
	v_pk_mul_f32 v[104:105], v[28:29], v[104:105]
	s_nop 0
	v_sub_f32_e32 v16, v16, v104
	v_sub_f32_e32 v16, v16, v105
	v_and_b32_e32 v104, 0xffff0000, v233
	v_lshlrev_b32_e32 v105, 16, v234
	v_pk_mul_f32 v[104:105], v[74:75], v[104:105]
	s_nop 0
	v_sub_f32_e32 v16, v16, v104
	v_sub_f32_e32 v16, v16, v105
	v_and_b32_e32 v104, 0xffff0000, v234
	v_lshlrev_b32_e32 v105, 16, v235
	v_pk_mul_f32 v[104:105], v[84:85], v[104:105]
	s_nop 0
	v_sub_f32_e32 v16, v16, v104
	v_sub_f32_e32 v105, v16, v105
	s_nop 0
	v_mov_b32_e32 v104, v85
	s_waitcnt lgkmcnt(0)
	ds_read_b128 v[232:235], v167 offset:5968
	ds_read_b32 v236, v167 offset:5984
	v_lshlrev_b32_e32 v128, 16, v242
	v_and_b32_e32 v129, 0xffff0000, v242
	v_pk_mul_f32 v[128:129], v[22:23], v[128:129]
	v_lshlrev_b32_e32 v124, 16, v243
	v_sub_f32_e32 v16, v66, v128
	v_and_b32_e32 v125, 0xffff0000, v243
	v_sub_f32_e32 v16, v16, v129
	v_pk_mul_f32 v[124:125], v[72:73], v[124:125]
	s_nop 0
	v_sub_f32_e32 v16, v16, v124
	v_sub_f32_e32 v16, v16, v125
	v_lshlrev_b32_e32 v124, 16, v244
	v_and_b32_e32 v125, 0xffff0000, v244
	v_pk_mul_f32 v[124:125], v[78:79], v[124:125]
	s_nop 0
	v_sub_f32_e32 v16, v16, v124
	v_sub_f32_e32 v16, v16, v125
	v_lshlrev_b32_e32 v124, 16, v245
	v_and_b32_e32 v125, 0xffff0000, v245
	v_pk_mul_f32 v[124:125], v[104:105], v[124:125]
	s_nop 0
	v_sub_f32_e32 v16, v16, v124
	v_sub_f32_e32 v125, v16, v125
	s_nop 0
	s_nop 0
	v_mov_b32_e32 v124, v105
	s_waitcnt lgkmcnt(0)
	ds_read_b128 v[242:245], v167 offset:6112
	ds_read_b32 v246, v167 offset:6128
	v_lshlrev_b32_e32 v18, 16, v232
	v_and_b32_e32 v130, 0xffff0000, v232
	v_lshlrev_b32_e32 v131, 16, v233
	v_fma_f32 v18, -v63, v18, v76
	v_pk_mul_f32 v[130:131], v[28:29], v[130:131]
	v_and_b32_e32 v126, 0xffff0000, v233
	v_sub_f32_e32 v18, v18, v130
	v_lshlrev_b32_e32 v127, 16, v234
	v_sub_f32_e32 v18, v18, v131
	v_pk_mul_f32 v[126:127], v[74:75], v[126:127]
	s_nop 0
	v_sub_f32_e32 v18, v18, v126
	v_sub_f32_e32 v18, v18, v127
	v_and_b32_e32 v126, 0xffff0000, v234
	v_lshlrev_b32_e32 v127, 16, v235
	v_pk_mul_f32 v[126:127], v[84:85], v[126:127]
	s_nop 0
	v_sub_f32_e32 v18, v18, v126
	v_sub_f32_e32 v18, v18, v127
	v_and_b32_e32 v126, 0xffff0000, v235
	s_waitcnt lgkmcnt(0)
	v_lshlrev_b32_e32 v127, 16, v236
	v_pk_mul_f32 v[126:127], v[124:125], v[126:127]
	s_nop 0
	v_sub_f32_e32 v16, v18, v126
	v_sub_f32_e32 v127, v16, v127
	s_nop 0
	s_nop 0
	v_mov_b32_e32 v126, v125
	s_waitcnt lgkmcnt(0)
	ds_read_b128 v[232:235], v167 offset:6256
	ds_read_b64 v[236:237], v167 offset:6272
	v_lshlrev_b32_e32 v132, 16, v242
	v_and_b32_e32 v133, 0xffff0000, v242
	v_pk_mul_f32 v[132:133], v[22:23], v[132:133]
	v_lshlrev_b32_e32 v128, 16, v243
	v_sub_f32_e32 v18, v94, v132
	v_and_b32_e32 v129, 0xffff0000, v243
	v_sub_f32_e32 v18, v18, v133
	v_pk_mul_f32 v[128:129], v[72:73], v[128:129]
	s_nop 0
	v_sub_f32_e32 v18, v18, v128
	v_sub_f32_e32 v18, v18, v129
	v_lshlrev_b32_e32 v128, 16, v244
	v_and_b32_e32 v129, 0xffff0000, v244
	v_pk_mul_f32 v[128:129], v[78:79], v[128:129]
	s_nop 0
	v_sub_f32_e32 v18, v18, v128
	v_sub_f32_e32 v18, v18, v129
	v_lshlrev_b32_e32 v128, 16, v245
	v_and_b32_e32 v129, 0xffff0000, v245
	v_pk_mul_f32 v[128:129], v[104:105], v[128:129]
	s_nop 0
	v_sub_f32_e32 v18, v18, v128
	v_sub_f32_e32 v18, v18, v129
	s_waitcnt lgkmcnt(0)
	v_lshlrev_b32_e32 v128, 16, v246
	v_and_b32_e32 v129, 0xffff0000, v246
	v_pk_mul_f32 v[128:129], v[126:127], v[128:129]
	s_nop 0
	v_sub_f32_e32 v16, v18, v128
	v_sub_f32_e32 v129, v16, v129
	s_nop 0
	s_nop 0
	v_mov_b32_e32 v128, v127
	s_waitcnt lgkmcnt(0)
	ds_read_b128 v[242:245], v167 offset:6400
	ds_read_b64 v[246:247], v167 offset:6416
	v_lshlrev_b32_e32 v16, 16, v232
	v_and_b32_e32 v136, 0xffff0000, v232
	v_lshlrev_b32_e32 v137, 16, v233
	v_fma_f32 v16, -v63, v16, v96
	v_pk_mul_f32 v[136:137], v[28:29], v[136:137]
	v_and_b32_e32 v130, 0xffff0000, v233
	v_sub_f32_e32 v16, v16, v136
	v_lshlrev_b32_e32 v131, 16, v234
	v_sub_f32_e32 v16, v16, v137
	v_pk_mul_f32 v[130:131], v[74:75], v[130:131]
	s_nop 0
	v_sub_f32_e32 v16, v16, v130
	v_sub_f32_e32 v16, v16, v131
	v_and_b32_e32 v130, 0xffff0000, v234
	v_lshlrev_b32_e32 v131, 16, v235
	v_pk_mul_f32 v[130:131], v[84:85], v[130:131]
	s_nop 0
	v_sub_f32_e32 v16, v16, v130
	v_sub_f32_e32 v16, v16, v131
	v_and_b32_e32 v130, 0xffff0000, v235
	s_waitcnt lgkmcnt(0)
	v_lshlrev_b32_e32 v131, 16, v236
	v_pk_mul_f32 v[130:131], v[124:125], v[130:131]
	s_nop 0
	v_sub_f32_e32 v16, v16, v130
	v_sub_f32_e32 v16, v16, v131
	v_and_b32_e32 v130, 0xffff0000, v236
	v_lshlrev_b32_e32 v131, 16, v237
	v_pk_mul_f32 v[130:131], v[128:129], v[130:131]
	s_nop 0
	v_sub_f32_e32 v16, v16, v130
	v_sub_f32_e32 v131, v16, v131
	s_nop 0
	s_nop 0
	v_mov_b32_e32 v130, v129
	s_waitcnt lgkmcnt(0)
	ds_read_b128 v[232:235], v167 offset:6544
	ds_read_b128 v[236:239], v167 offset:6560
	v_lshlrev_b32_e32 v16, 16, v242
	v_and_b32_e32 v18, 0xffff0000, v242
	v_fma_f32 v16, -v63, v16, v100
	v_lshlrev_b32_e32 v132, 16, v243
	v_and_b32_e32 v133, 0xffff0000, v243
	v_fma_f32 v16, -v23, v18, v16
	v_pk_mul_f32 v[132:133], v[72:73], v[132:133]
	s_nop 0
	v_sub_f32_e32 v16, v16, v132
	v_sub_f32_e32 v16, v16, v133
	v_lshlrev_b32_e32 v132, 16, v244
	v_and_b32_e32 v133, 0xffff0000, v244
	v_pk_mul_f32 v[132:133], v[78:79], v[132:133]
	s_nop 0
	v_sub_f32_e32 v16, v16, v132
	v_sub_f32_e32 v16, v16, v133
	v_lshlrev_b32_e32 v132, 16, v245
	v_and_b32_e32 v133, 0xffff0000, v245
	v_pk_mul_f32 v[132:133], v[104:105], v[132:133]
	s_nop 0
	v_sub_f32_e32 v16, v16, v132
	v_sub_f32_e32 v16, v16, v133
	s_waitcnt lgkmcnt(0)
	v_lshlrev_b32_e32 v132, 16, v246
	v_and_b32_e32 v133, 0xffff0000, v246
	v_pk_mul_f32 v[132:133], v[126:127], v[132:133]
	s_nop 0
	v_sub_f32_e32 v16, v16, v132
	v_sub_f32_e32 v16, v16, v133
	v_lshlrev_b32_e32 v132, 16, v247
	v_and_b32_e32 v133, 0xffff0000, v247
	v_pk_mul_f32 v[132:133], v[130:131], v[132:133]
	s_nop 0
	v_sub_f32_e32 v16, v16, v132
	v_sub_f32_e32 v133, v16, v133
	s_nop 0
	s_nop 0
	v_mov_b32_e32 v132, v131
	s_waitcnt lgkmcnt(0)
	ds_read_b128 v[242:245], v167 offset:6688
	ds_read_b96 v[246:248], v167 offset:6704
	v_lshlrev_b32_e32 v16, 16, v232
	v_and_b32_e32 v18, 0xffff0000, v232
	v_fma_f32 v16, -v63, v16, v102
	v_lshlrev_b32_e32 v20, 16, v233
	v_fma_f32 v16, -v23, v18, v16
	v_and_b32_e32 v134, 0xffff0000, v233
	v_lshlrev_b32_e32 v135, 16, v234
	v_fma_f32 v16, -v29, v20, v16
	v_pk_mul_f32 v[134:135], v[74:75], v[134:135]
	s_nop 0
	v_sub_f32_e32 v16, v16, v134
	v_sub_f32_e32 v16, v16, v135
	v_and_b32_e32 v134, 0xffff0000, v234
	v_lshlrev_b32_e32 v135, 16, v235
	v_pk_mul_f32 v[134:135], v[84:85], v[134:135]
	s_nop 0
	v_sub_f32_e32 v16, v16, v134
	v_sub_f32_e32 v16, v16, v135
	v_and_b32_e32 v134, 0xffff0000, v235
	s_waitcnt lgkmcnt(0)
	v_lshlrev_b32_e32 v135, 16, v236
	v_pk_mul_f32 v[134:135], v[124:125], v[134:135]
	s_nop 0
	v_sub_f32_e32 v16, v16, v134
	v_sub_f32_e32 v16, v16, v135
	v_and_b32_e32 v134, 0xffff0000, v236
	v_lshlrev_b32_e32 v135, 16, v237
	v_pk_mul_f32 v[134:135], v[128:129], v[134:135]
	s_nop 0
	v_sub_f32_e32 v16, v16, v134
	v_sub_f32_e32 v16, v16, v135
	v_and_b32_e32 v134, 0xffff0000, v237
	v_lshlrev_b32_e32 v135, 16, v238
	v_pk_mul_f32 v[134:135], v[132:133], v[134:135]
	s_nop 0
	v_sub_f32_e32 v16, v16, v134
	v_sub_f32_e32 v135, v16, v135
	s_nop 0
	s_nop 0
	v_mov_b32_e32 v134, v133
	s_waitcnt lgkmcnt(0)
	ds_read_b128 v[232:235], v167 offset:6832
	ds_read_b128 v[236:239], v167 offset:6848
	v_lshlrev_b32_e32 v16, 16, v242
	v_and_b32_e32 v18, 0xffff0000, v242
	v_fma_f32 v14, -v63, v16, v14
	v_lshlrev_b32_e32 v20, 16, v243
	v_fma_f32 v14, -v23, v18, v14
	v_and_b32_e32 v22, 0xffff0000, v243
	v_fma_f32 v14, -v29, v20, v14
	v_lshlrev_b32_e32 v136, 16, v244
	v_and_b32_e32 v137, 0xffff0000, v244
	v_fma_f32 v14, -v73, v22, v14
	v_pk_mul_f32 v[136:137], v[78:79], v[136:137]
	s_nop 0
	v_sub_f32_e32 v14, v14, v136
	v_sub_f32_e32 v14, v14, v137
	v_lshlrev_b32_e32 v136, 16, v245
	v_and_b32_e32 v137, 0xffff0000, v245
	v_pk_mul_f32 v[136:137], v[104:105], v[136:137]
	s_nop 0
	v_sub_f32_e32 v14, v14, v136
	v_sub_f32_e32 v14, v14, v137
	s_waitcnt lgkmcnt(0)
	v_lshlrev_b32_e32 v136, 16, v246
	v_and_b32_e32 v137, 0xffff0000, v246
	v_pk_mul_f32 v[136:137], v[126:127], v[136:137]
	s_nop 0
	v_sub_f32_e32 v14, v14, v136
	v_sub_f32_e32 v14, v14, v137
	v_lshlrev_b32_e32 v136, 16, v247
	v_and_b32_e32 v137, 0xffff0000, v247
	v_pk_mul_f32 v[136:137], v[130:131], v[136:137]
	s_nop 0
	v_sub_f32_e32 v14, v14, v136
	v_sub_f32_e32 v14, v14, v137
	v_lshlrev_b32_e32 v136, 16, v248
	v_and_b32_e32 v137, 0xffff0000, v248
	v_pk_mul_f32 v[136:137], v[134:135], v[136:137]
	s_nop 0
	v_sub_f32_e32 v14, v14, v136
	v_sub_f32_e32 v137, v14, v137
	s_nop 0
	s_nop 0
	v_mov_b32_e32 v136, v135
	s_waitcnt lgkmcnt(0)
	ds_read_b32 v242, v167 offset:7152
	v_lshlrev_b32_e32 v14, 16, v232
	v_and_b32_e32 v16, 0xffff0000, v232
	v_fma_f32 v12, -v63, v14, v12
	v_lshlrev_b32_e32 v18, 16, v233
	v_fma_f32 v12, -v23, v16, v12
	v_and_b32_e32 v20, 0xffff0000, v233
	v_fma_f32 v12, -v29, v18, v12
	v_lshlrev_b32_e32 v22, 16, v234
	v_fma_f32 v12, -v73, v20, v12
	v_and_b32_e32 v152, 0xffff0000, v234
	v_lshlrev_b32_e32 v153, 16, v235
	v_fma_f32 v12, -v75, v22, v12
	v_pk_mul_f32 v[152:153], v[84:85], v[152:153]
	v_cvt_pk_bf16_f32 v192, v63, v23
	v_cvt_pk_bf16_f32 v193, v29, v73
	v_cvt_pk_bf16_f32 v194, v75, v79
	s_nop 0
	v_sub_f32_e32 v12, v12, v152
	v_sub_f32_e32 v12, v12, v153
	v_and_b32_e32 v152, 0xffff0000, v235
	s_waitcnt lgkmcnt(0)
	v_lshlrev_b32_e32 v153, 16, v236
	v_pk_mul_f32 v[152:153], v[124:125], v[152:153]
	v_cvt_pk_bf16_f32 v195, v85, v105
	s_nop 0
	v_sub_f32_e32 v12, v12, v152
	v_sub_f32_e32 v12, v12, v153
	v_and_b32_e32 v152, 0xffff0000, v236
	v_lshlrev_b32_e32 v153, 16, v237
	v_pk_mul_f32 v[152:153], v[128:129], v[152:153]
	s_nop 0
	v_sub_f32_e32 v12, v12, v152
	v_sub_f32_e32 v12, v12, v153
	v_and_b32_e32 v152, 0xffff0000, v237
	v_lshlrev_b32_e32 v153, 16, v238
	v_pk_mul_f32 v[152:153], v[132:133], v[152:153]
	s_nop 0
	v_sub_f32_e32 v12, v12, v152
	v_sub_f32_e32 v12, v12, v153
	v_and_b32_e32 v152, 0xffff0000, v238
	v_lshlrev_b32_e32 v153, 16, v239
	v_pk_mul_f32 v[152:153], v[136:137], v[152:153]
	s_nop 0
	v_sub_f32_e32 v12, v12, v152
	v_sub_f32_e32 v12, v12, v153
	ds_write_b128 v186, v[192:195] offset:64
	v_cvt_pk_bf16_f32 v192, v125, v127
	v_cvt_pk_bf16_f32 v193, v129, v131
	v_cvt_pk_bf16_f32 v194, v133, v135
	v_cvt_pk_bf16_f32 v195, v137, v12
	ds_write_b128 v186, v[192:195] offset:80
	s_waitcnt lgkmcnt(0)
	ds_read_b128 v[192:195], v187 offset:4608
	ds_read_b128 v[212:215], v188
	ds_read_b128 v[216:219], v188 offset:2304
	ds_read_b128 v[228:231], v188 offset:64
	ds_read_b128 v[220:223], v188 offset:4608
	ds_read_b128 v[224:227], v188 offset:6912
	s_waitcnt lgkmcnt(0)
	v_mfma_f32_16x16x32_bf16 v[212:215], v[192:195], v[212:215], 0
	s_waitcnt lgkmcnt(3)
	v_mfma_f32_16x16x32_bf16 v[216:219], v[192:195], v[216:219], 0
	s_waitcnt lgkmcnt(1)
	v_mfma_f32_16x16x32_bf16 v[220:223], v[192:195], v[220:223], 0
	s_waitcnt lgkmcnt(0)
	v_mfma_f32_16x16x32_bf16 v[192:195], v[192:195], v[224:227], 0
	ds_read_b128 v[224:227], v187 offset:4672
	s_waitcnt lgkmcnt(0)
	v_cndmask_b32_e64 v227, 0, v227, s[54:55]
	v_cndmask_b32_e64 v226, 0, v226, s[54:55]
	v_cndmask_b32_e64 v225, 0, v225, s[54:55]
	v_cndmask_b32_e64 v224, 0, v224, s[54:55]
	s_nop 1
	v_mfma_f32_16x16x32_bf16 v[212:215], v[224:227], v[228:231], v[212:215]
	ds_read_b128 v[228:231], v188 offset:2368
	s_waitcnt lgkmcnt(0)
	v_mfma_f32_16x16x32_bf16 v[216:219], v[224:227], v[228:231], v[216:219]
	ds_read_b128 v[228:231], v188 offset:4672
	s_waitcnt lgkmcnt(0)
	v_mfma_f32_16x16x32_bf16 v[220:223], v[224:227], v[228:231], v[220:223]
	ds_read_b128 v[228:231], v188 offset:6976
	s_waitcnt lgkmcnt(0)
	v_mfma_f32_16x16x32_bf16 v[192:195], v[224:227], v[228:231], v[192:195]
	s_nop 1
	ds_write2_b32 v189, v212, v216 offset1:16
	ds_write2_b32 v6, v213, v217 offset1:16
	ds_write2_b32 v8, v214, v218 offset1:16
	ds_write2_b32 v10, v215, v219 offset1:16
	s_nop 1
	ds_write2_b32 v189, v220, v192 offset0:32 offset1:48
	ds_write2_b32 v6, v221, v193 offset0:32 offset1:48
	ds_write2_b32 v8, v222, v194 offset0:32 offset1:48
	ds_write2_b32 v10, v223, v195 offset0:32 offset1:48
	s_waitcnt lgkmcnt(0)
	ds_read2st64_b32 v[152:153], v178 offset1:4
	s_waitcnt lgkmcnt(0)
	v_sub_f32_e32 v6, v64, v152
	v_sub_f32_e32 v8, v65, v153
	ds_read2st64_b32 v[64:65], v178 offset0:8 offset1:12
	s_waitcnt lgkmcnt(0)
	v_sub_f32_e32 v10, v68, v64
	v_sub_f32_e32 v14, v69, v65
	ds_read2st64_b32 v[64:65], v178 offset0:16 offset1:20
	s_waitcnt lgkmcnt(0)
	v_sub_f32_e32 v16, v70, v64
	v_sub_f32_e32 v18, v71, v65
	ds_read2st64_b32 v[64:65], v178 offset0:24 offset1:28
	s_waitcnt lgkmcnt(0)
	v_sub_f32_e32 v20, v80, v64
	v_sub_f32_e32 v24, v81, v65
	ds_read2st64_b32 v[64:65], v178 offset0:32 offset1:36
	s_waitcnt lgkmcnt(0)
	v_sub_f32_e32 v26, v82, v64
	v_sub_f32_e32 v28, v83, v65
	ds_read2st64_b32 v[64:65], v178 offset0:40 offset1:44
	s_waitcnt lgkmcnt(0)
	v_sub_f32_e32 v30, v92, v64
	v_sub_f32_e32 v62, v93, v65
	ds_read2st64_b32 v[64:65], v178 offset0:48 offset1:52
	s_waitcnt lgkmcnt(0)
	v_sub_f32_e32 v66, v98, v64
	v_sub_f32_e32 v72, v99, v65
	ds_read2st64_b32 v[64:65], v178 offset0:56 offset1:60
	s_waitcnt lgkmcnt(0)
	v_sub_f32_e32 v74, v108, v64
	v_sub_f32_e32 v76, v109, v65
	s_nop 0
	s_waitcnt lgkmcnt(0)
	ds_read_b32 v232, v167 offset:7296
	v_lshlrev_b32_e32 v22, 16, v242
	v_fma_f32 v8, -v6, v22, v8
	s_nop 0
	s_waitcnt lgkmcnt(0)
	ds_read_b128 v[242:245], v167 offset:7440
	v_and_b32_e32 v64, 0xffff0000, v232
	v_lshlrev_b32_e32 v22, 16, v232
	v_fma_f32 v10, -v6, v22, v10
	v_fma_f32 v10, -v8, v64, v10
	s_nop 0
	s_waitcnt lgkmcnt(0)
	ds_read_b128 v[232:235], v167 offset:7584
	v_lshlrev_b32_e32 v65, 16, v242
	v_and_b32_e32 v64, 0xffff0000, v242
	v_fma_f32 v14, -v6, v65, v14
	v_lshlrev_b32_e32 v22, 16, v243
	v_fma_f32 v14, -v8, v64, v14
	v_fma_f32 v14, -v10, v22, v14
	s_nop 0
	s_waitcnt lgkmcnt(0)
	ds_read_b128 v[242:245], v167 offset:7728
	v_and_b32_e32 v65, 0xffff0000, v232
	v_lshlrev_b32_e32 v68, 16, v232
	v_fma_f32 v16, -v6, v68, v16
	v_lshlrev_b32_e32 v64, 16, v233
	v_fma_f32 v16, -v8, v65, v16
	v_and_b32_e32 v22, 0xffff0000, v233
	v_fma_f32 v16, -v10, v64, v16
	v_fma_f32 v16, -v14, v22, v16
	s_nop 0
	s_waitcnt lgkmcnt(0)
	ds_read_b128 v[232:235], v167 offset:7872
	v_and_b32_e32 v64, 0xffff0000, v243
	v_lshlrev_b32_e32 v65, 16, v243
	v_and_b32_e32 v69, 0xffff0000, v242
	v_lshlrev_b32_e32 v68, 16, v242
	v_fma_f32 v18, -v6, v68, v18
	v_fma_f32 v18, -v8, v69, v18
	v_fma_f32 v18, -v10, v65, v18
	v_lshlrev_b32_e32 v22, 16, v244
	v_fma_f32 v18, -v14, v64, v18
	v_fma_f32 v18, -v16, v22, v18
	s_nop 0
	s_waitcnt lgkmcnt(0)
	ds_read_b128 v[242:245], v167 offset:8016
	v_and_b32_e32 v22, 0xffff0000, v234
	v_lshlrev_b32_e32 v64, 16, v234
	v_and_b32_e32 v70, 0xffff0000, v232
	v_lshlrev_b32_e32 v68, 16, v232
	v_fma_f32 v20, -v6, v68, v20
	v_and_b32_e32 v65, 0xffff0000, v233
	v_lshlrev_b32_e32 v69, 16, v233
	v_fma_f32 v20, -v8, v70, v20
	v_fma_f32 v20, -v10, v69, v20
	v_fma_f32 v20, -v14, v65, v20
	v_fma_f32 v20, -v16, v64, v20
	v_fma_f32 v22, -v18, v22, v20
	s_nop 0
	s_waitcnt lgkmcnt(0)
	ds_read_b128 v[232:235], v167 offset:8160
	v_lshlrev_b32_e32 v20, 16, v245
	v_and_b32_e32 v71, 0xffff0000, v242
	v_lshlrev_b32_e32 v68, 16, v242
	v_fma_f32 v24, -v6, v68, v24
	v_and_b32_e32 v64, 0xffff0000, v244
	v_lshlrev_b32_e32 v65, 16, v244
	v_and_b32_e32 v70, 0xffff0000, v243
	v_lshlrev_b32_e32 v69, 16, v243
	v_fma_f32 v24, -v8, v71, v24
	v_fma_f32 v24, -v10, v69, v24
	v_fma_f32 v24, -v14, v70, v24
	v_fma_f32 v24, -v16, v65, v24
	v_fma_f32 v24, -v18, v64, v24
	v_fma_f32 v24, -v22, v20, v24
	s_nop 0
	s_waitcnt lgkmcnt(0)
	ds_read_b128 v[242:245], v167 offset:8304
	ds_read_b32 v246, v167 offset:8320
	v_and_b32_e32 v78, 0xffff0000, v232
	v_lshlrev_b32_e32 v68, 16, v232
	v_fma_f32 v26, -v6, v68, v26
	v_and_b32_e32 v20, 0xffff0000, v235
	v_lshlrev_b32_e32 v64, 16, v235
	v_and_b32_e32 v71, 0xffff0000, v233
	v_lshlrev_b32_e32 v69, 16, v233
	v_fma_f32 v26, -v8, v78, v26
	v_fma_f32 v26, -v10, v69, v26
	v_and_b32_e32 v65, 0xffff0000, v234
	v_lshlrev_b32_e32 v70, 16, v234
	v_fma_f32 v26, -v14, v71, v26
	v_fma_f32 v26, -v16, v70, v26
	v_fma_f32 v26, -v18, v65, v26
	v_fma_f32 v26, -v22, v64, v26
	v_fma_f32 v26, -v24, v20, v26
	s_nop 0
	s_nop 0
	s_waitcnt lgkmcnt(0)
	ds_read_b128 v[232:235], v167 offset:8448
	ds_read_b32 v236, v167 offset:8464
	v_lshlrev_b32_e32 v64, 16, v242
	v_and_b32_e32 v65, 0xffff0000, v242
	v_fma_f32 v28, -v6, v64, v28
	v_lshlrev_b32_e32 v68, 16, v243
	v_fma_f32 v28, -v8, v65, v28
	v_and_b32_e32 v69, 0xffff0000, v243
	v_fma_f32 v28, -v10, v68, v28
	v_lshlrev_b32_e32 v78, 16, v244
	v_fma_f32 v28, -v14, v69, v28
	v_and_b32_e32 v70, 0xffff0000, v244
	v_fma_f32 v28, -v16, v78, v28
	v_lshlrev_b32_e32 v80, 16, v245
	v_fma_f32 v28, -v18, v70, v28
	v_and_b32_e32 v71, 0xffff0000, v245
	v_fma_f32 v28, -v22, v80, v28
	s_waitcnt lgkmcnt(0)
	v_lshlrev_b32_e32 v20, 16, v246
	v_fma_f32 v28, -v24, v71, v28
	v_fma_f32 v28, -v26, v20, v28
	s_nop 0
	s_nop 0
	s_waitcnt lgkmcnt(0)
	ds_read_b128 v[242:245], v167 offset:8592
	ds_read_b128 v[246:249], v167 offset:8608
	v_lshlrev_b32_e32 v64, 16, v232
	v_and_b32_e32 v65, 0xffff0000, v232
	v_fma_f32 v30, -v6, v64, v30
	v_lshlrev_b32_e32 v68, 16, v233
	v_fma_f32 v30, -v8, v65, v30
	v_and_b32_e32 v69, 0xffff0000, v233
	v_fma_f32 v30, -v10, v68, v30
	v_lshlrev_b32_e32 v78, 16, v234
	v_fma_f32 v30, -v14, v69, v30
	v_and_b32_e32 v70, 0xffff0000, v234
	v_fma_f32 v30, -v16, v78, v30
	v_lshlrev_b32_e32 v80, 16, v235
	v_fma_f32 v30, -v18, v70, v30
	v_and_b32_e32 v71, 0xffff0000, v235
	v_fma_f32 v30, -v22, v80, v30
	s_waitcnt lgkmcnt(0)
	v_and_b32_e32 v81, 0xffff0000, v236
	v_lshlrev_b32_e32 v20, 16, v236
	v_fma_f32 v30, -v24, v71, v30
	v_fma_f32 v20, -v26, v20, v30
	v_fma_f32 v30, -v28, v81, v20
	s_nop 0
	s_nop 0
	s_waitcnt lgkmcnt(0)
	ds_read_b128 v[232:235], v167 offset:8736
	ds_read_b128 v[236:239], v167 offset:8752
	v_lshlrev_b32_e32 v20, 16, v242
	v_and_b32_e32 v64, 0xffff0000, v242
	v_fma_f32 v20, -v6, v20, v62
	v_lshlrev_b32_e32 v65, 16, v243
	v_fma_f32 v20, -v8, v64, v20
	v_and_b32_e32 v68, 0xffff0000, v243
	v_fma_f32 v20, -v10, v65, v20
	v_lshlrev_b32_e32 v69, 16, v244
	v_fma_f32 v20, -v14, v68, v20
	v_and_b32_e32 v70, 0xffff0000, v244
	v_fma_f32 v20, -v16, v69, v20
	v_lshlrev_b32_e32 v78, 16, v245
	v_fma_f32 v20, -v18, v70, v20
	v_and_b32_e32 v71, 0xffff0000, v245
	v_fma_f32 v20, -v22, v78, v20
	s_waitcnt lgkmcnt(0)
	v_and_b32_e32 v82, 0xffff0000, v246
	v_lshlrev_b32_e32 v80, 16, v246
	v_fma_f32 v20, -v24, v71, v20
	v_fma_f32 v20, -v26, v80, v20
	v_lshlrev_b32_e32 v81, 16, v247
	v_fma_f32 v20, -v28, v82, v20
	v_fma_f32 v64, -v30, v81, v20
	s_nop 0
	s_nop 0
	s_waitcnt lgkmcnt(0)
	ds_read_b128 v[242:245], v167 offset:8880
	ds_read_b128 v[246:249], v167 offset:8896
	v_lshlrev_b32_e32 v20, 16, v232
	v_and_b32_e32 v62, 0xffff0000, v232
	v_fma_f32 v20, -v6, v20, v66
	v_lshlrev_b32_e32 v65, 16, v233
	v_fma_f32 v20, -v8, v62, v20
	v_and_b32_e32 v68, 0xffff0000, v233
	v_fma_f32 v20, -v10, v65, v20
	v_lshlrev_b32_e32 v69, 16, v234
	v_fma_f32 v20, -v14, v68, v20
	v_and_b32_e32 v70, 0xffff0000, v234
	v_fma_f32 v20, -v16, v69, v20
	v_lshlrev_b32_e32 v78, 16, v235
	v_fma_f32 v20, -v18, v70, v20
	v_and_b32_e32 v71, 0xffff0000, v235
	v_fma_f32 v20, -v22, v78, v20
	s_waitcnt lgkmcnt(0)
	v_and_b32_e32 v83, 0xffff0000, v236
	v_lshlrev_b32_e32 v80, 16, v236
	v_fma_f32 v20, -v24, v71, v20
	v_fma_f32 v20, -v26, v80, v20
	v_and_b32_e32 v82, 0xffff0000, v237
	v_lshlrev_b32_e32 v81, 16, v237
	v_fma_f32 v20, -v28, v83, v20
	v_fma_f32 v20, -v30, v81, v20
	v_fma_f32 v65, -v64, v82, v20
	s_nop 0
	s_nop 0
	s_waitcnt lgkmcnt(0)
	ds_read_b128 v[232:235], v167 offset:9024
	ds_read_b128 v[236:239], v167 offset:9040
	v_lshlrev_b32_e32 v20, 16, v242
	v_and_b32_e32 v62, 0xffff0000, v242
	v_fma_f32 v20, -v6, v20, v72
	v_lshlrev_b32_e32 v66, 16, v243
	v_fma_f32 v20, -v8, v62, v20
	v_and_b32_e32 v68, 0xffff0000, v243
	v_fma_f32 v20, -v10, v66, v20
	v_lshlrev_b32_e32 v69, 16, v244
	v_fma_f32 v20, -v14, v68, v20
	v_and_b32_e32 v70, 0xffff0000, v244
	v_fma_f32 v20, -v16, v69, v20
	v_lshlrev_b32_e32 v78, 16, v245
	v_fma_f32 v20, -v18, v70, v20
	v_and_b32_e32 v71, 0xffff0000, v245
	v_fma_f32 v20, -v22, v78, v20
	s_waitcnt lgkmcnt(0)
	v_and_b32_e32 v84, 0xffff0000, v246
	v_lshlrev_b32_e32 v80, 16, v246
	v_fma_f32 v20, -v24, v71, v20
	v_fma_f32 v20, -v26, v80, v20
	v_and_b32_e32 v83, 0xffff0000, v247
	v_lshlrev_b32_e32 v81, 16, v247
	v_fma_f32 v20, -v28, v84, v20
	v_fma_f32 v20, -v30, v81, v20
	v_lshlrev_b32_e32 v82, 16, v248
	v_fma_f32 v20, -v64, v83, v20
	v_fma_f32 v66, -v65, v82, v20
	s_nop 0
	s_nop 0
	s_waitcnt lgkmcnt(0)
	ds_read_b128 v[242:245], v167 offset:9168
	ds_read_b128 v[246:249], v167 offset:9184
	v_lshlrev_b32_e32 v20, 16, v232
	v_and_b32_e32 v62, 0xffff0000, v232
	v_fma_f32 v20, -v6, v20, v74
	v_lshlrev_b32_e32 v68, 16, v233
	v_fma_f32 v20, -v8, v62, v20
	v_and_b32_e32 v69, 0xffff0000, v233
	v_fma_f32 v20, -v10, v68, v20
	v_lshlrev_b32_e32 v72, 16, v234
	v_fma_f32 v20, -v14, v69, v20
	v_and_b32_e32 v70, 0xffff0000, v234
	v_fma_f32 v20, -v16, v72, v20
	v_lshlrev_b32_e32 v78, 16, v235
	v_fma_f32 v20, -v18, v70, v20
	v_and_b32_e32 v71, 0xffff0000, v235
	v_fma_f32 v20, -v22, v78, v20
	s_waitcnt lgkmcnt(0)
	v_and_b32_e32 v86, 0xffff0000, v236
	v_lshlrev_b32_e32 v80, 16, v236
	v_fma_f32 v20, -v24, v71, v20
	v_fma_f32 v20, -v26, v80, v20
	v_and_b32_e32 v84, 0xffff0000, v237
	v_lshlrev_b32_e32 v81, 16, v237
	v_fma_f32 v20, -v28, v86, v20
	v_fma_f32 v20, -v30, v81, v20
	v_and_b32_e32 v83, 0xffff0000, v238
	v_lshlrev_b32_e32 v82, 16, v238
	v_fma_f32 v20, -v64, v84, v20
	v_fma_f32 v20, -v65, v82, v20
	v_fma_f32 v68, -v66, v83, v20
	s_nop 0
	s_nop 0
	s_waitcnt lgkmcnt(0)
	v_lshlrev_b32_e32 v20, 16, v242
	v_and_b32_e32 v62, 0xffff0000, v242
	v_fma_f32 v20, -v6, v20, v76
	v_lshlrev_b32_e32 v69, 16, v243
	v_fma_f32 v20, -v8, v62, v20
	v_and_b32_e32 v70, 0xffff0000, v243
	v_fma_f32 v20, -v10, v69, v20
	v_lshlrev_b32_e32 v71, 16, v244
	v_fma_f32 v20, -v14, v70, v20
	v_and_b32_e32 v72, 0xffff0000, v244
	v_fma_f32 v20, -v16, v71, v20
	v_lshlrev_b32_e32 v74, 16, v245
	v_fma_f32 v20, -v18, v72, v20
	v_and_b32_e32 v78, 0xffff0000, v245
	v_fma_f32 v20, -v22, v74, v20
	s_waitcnt lgkmcnt(0)
	v_lshlrev_b32_e32 v92, 16, v246
	v_fma_f32 v20, -v24, v78, v20
	v_and_b32_e32 v86, 0xffff0000, v246
	v_fma_f32 v20, -v26, v92, v20
	v_lshlrev_b32_e32 v84, 16, v247
	v_fma_f32 v20, -v28, v86, v20
	v_and_b32_e32 v83, 0xffff0000, v247
	v_fma_f32 v20, -v30, v84, v20
	v_lshlrev_b32_e32 v82, 16, v248
	v_fma_f32 v20, -v64, v83, v20
	v_and_b32_e32 v81, 0xffff0000, v248
	v_fma_f32 v20, -v65, v82, v20
	v_lshlrev_b32_e32 v80, 16, v249
	v_fma_f32 v20, -v66, v81, v20
	v_fma_f32 v69, -v68, v80, v20
	s_and_saveexec_b64 s[36:37], s[42:43]
	s_xor_b64 s[44:45], exec, s[36:37]
	s_cbranch_execz .LBB0_365
	s_add_u32 s28, s74, s28
	s_addc_u32 s29, s75, s29
	v_lshl_add_u64 v[70:71], s[28:29], 0, v[56:57]
	v_add_co_u32_e32 v80, vcc, 0x31f40000, v70
	v_cvt_pk_bf16_f32 v0, v0, v0
	s_mov_b32 s8, 0x31f41000
	s_nop 0
	v_addc_co_u32_e32 v81, vcc, 0, v71, vcc
	global_store_short v[80:81], v0, off offset:3840
	v_add_co_u32_e32 v0, vcc, s8, v70
	v_cvt_pk_bf16_f32 v20, v1, v1
	v_cvt_pk_bf16_f32 v3, v3, v3
	s_mov_b32 s28, 0x31f42000
	s_nop 0
	v_addc_co_u32_e32 v1, vcc, 0, v71, vcc
	global_store_short v[0:1], v3, off offset:512
	v_cvt_pk_bf16_f32 v3, v95, v95
	global_store_short v[0:1], v3, off offset:768
	v_cvt_pk_bf16_f32 v3, v5, v5
	global_store_short v[0:1], v3, off offset:1024
	v_cvt_pk_bf16_f32 v3, v97, v97
	global_store_short v[0:1], v3, off offset:1280
	v_cvt_pk_bf16_f32 v3, v13, v13
	global_store_short v[0:1], v3, off offset:1536
	v_cvt_pk_bf16_f32 v3, v101, v101
	global_store_short v[0:1], v3, off offset:1792
	v_cvt_pk_bf16_f32 v3, v7, v7
	global_store_short v[0:1], v3, off offset:2048
	v_cvt_pk_bf16_f32 v3, v103, v103
	global_store_short v[0:1], v3, off offset:2304
	v_cvt_pk_bf16_f32 v3, v9, v9
	v_add_co_u32_e32 v80, vcc, s28, v70
	global_store_short v[0:1], v3, off offset:2560
	v_cvt_pk_bf16_f32 v3, v107, v107
	s_nop 0
	v_addc_co_u32_e32 v81, vcc, 0, v71, vcc
	global_store_short v[0:1], v3, off offset:2816
	v_cvt_pk_bf16_f32 v3, v11, v11
	v_cvt_pk_bf16_f32 v2, v2, v2
	global_store_short v[80:81], v20, off offset:-4096
	v_cvt_pk_bf16_f32 v20, v87, v87
	global_store_short v[0:1], v20, off offset:256
	global_store_short v[0:1], v3, off offset:3072
	v_cvt_pk_bf16_f32 v3, v111, v111
	global_store_short v[0:1], v3, off offset:3328
	global_store_short v[0:1], v2, off offset:3584
	v_cvt_pk_bf16_f32 v2, v21, v21
	global_store_short v[0:1], v2, off offset:3840
	v_cvt_pk_bf16_f32 v0, v15, v15
	global_store_short v[80:81], v0, off
	v_cvt_pk_bf16_f32 v0, v17, v17
	global_store_short v[80:81], v0, off offset:256
	v_cvt_pk_bf16_f32 v0, v19, v19
	global_store_short v[80:81], v0, off offset:512
	v_cvt_pk_bf16_f32 v0, v25, v25
	global_store_short v[80:81], v0, off offset:768
	v_cvt_pk_bf16_f32 v0, v27, v27
	global_store_short v[80:81], v0, off offset:1024
	v_cvt_pk_bf16_f32 v0, v31, v31
	global_store_short v[80:81], v0, off offset:1280
	v_cvt_pk_bf16_f32 v0, v67, v67
	global_store_short v[80:81], v0, off offset:1536
	v_cvt_pk_bf16_f32 v0, v77, v77
	global_store_short v[80:81], v0, off offset:1792
	v_cvt_pk_bf16_f32 v0, v113, v113
	global_store_short v[80:81], v0, off offset:2048
	v_cvt_pk_bf16_f32 v0, v115, v115
	global_store_short v[80:81], v0, off offset:2304
	v_cvt_pk_bf16_f32 v0, v117, v117
	global_store_short v[80:81], v0, off offset:2560
	v_cvt_pk_bf16_f32 v0, v119, v119
	global_store_short v[80:81], v0, off offset:2816
	v_cvt_pk_bf16_f32 v0, v121, v121
	global_store_short v[80:81], v0, off offset:3072
	v_cvt_pk_bf16_f32 v0, v123, v123
	global_store_short v[80:81], v0, off offset:3328
	v_cvt_pk_bf16_f32 v0, v4, v4
	global_store_short v[80:81], v0, off offset:3584
	v_cvt_pk_bf16_f32 v0, v63, v63
	s_mov_b32 s28, 0x31f43000
	global_store_short v[80:81], v0, off offset:3840
	v_add_co_u32_e32 v0, vcc, s28, v70
	s_mov_b32 s28, 0x31f44000
	s_nop 0
	v_addc_co_u32_e32 v1, vcc, 0, v71, vcc
	v_add_co_u32_e32 v2, vcc, s28, v70
	v_cvt_pk_bf16_f32 v4, v23, v23
	s_nop 1
	v_addc_co_u32_e32 v3, vcc, 0, v71, vcc
	global_store_short v[2:3], v4, off offset:-4096
	v_cvt_pk_bf16_f32 v4, v29, v29
	global_store_short v[0:1], v4, off offset:256
	v_cvt_pk_bf16_f32 v4, v73, v73
	global_store_short v[0:1], v4, off offset:512
	v_cvt_pk_bf16_f32 v4, v75, v75
	global_store_short v[0:1], v4, off offset:768
	v_cvt_pk_bf16_f32 v4, v79, v79
	global_store_short v[0:1], v4, off offset:1024
	v_cvt_pk_bf16_f32 v4, v85, v85
	global_store_short v[0:1], v4, off offset:1280
	v_cvt_pk_bf16_f32 v4, v105, v105
	global_store_short v[0:1], v4, off offset:1536
	v_cvt_pk_bf16_f32 v4, v125, v125
	global_store_short v[0:1], v4, off offset:1792
	v_cvt_pk_bf16_f32 v4, v127, v127
	global_store_short v[0:1], v4, off offset:2048
	v_cvt_pk_bf16_f32 v4, v129, v129
	global_store_short v[0:1], v4, off offset:2304
	v_cvt_pk_bf16_f32 v4, v131, v131
	global_store_short v[0:1], v4, off offset:2560
	v_cvt_pk_bf16_f32 v4, v133, v133
	global_store_short v[0:1], v4, off offset:2816
	v_cvt_pk_bf16_f32 v4, v135, v135
	global_store_short v[0:1], v4, off offset:3072
	v_cvt_pk_bf16_f32 v4, v137, v137
	global_store_short v[0:1], v4, off offset:3328
	v_cvt_pk_bf16_f32 v4, v12, v12
	global_store_short v[0:1], v4, off offset:3584
	v_cvt_pk_bf16_f32 v4, v6, v6
	global_store_short v[0:1], v4, off offset:3840
	v_cvt_pk_bf16_f32 v0, v8, v8
	global_store_short v[2:3], v0, off
	v_cvt_pk_bf16_f32 v0, v10, v10
	global_store_short v[2:3], v0, off offset:256
	v_cvt_pk_bf16_f32 v0, v14, v14
	global_store_short v[2:3], v0, off offset:512
	v_cvt_pk_bf16_f32 v0, v16, v16
	global_store_short v[2:3], v0, off offset:768
	v_cvt_pk_bf16_f32 v0, v18, v18
	global_store_short v[2:3], v0, off offset:1024
	v_cvt_pk_bf16_f32 v0, v22, v22
	global_store_short v[2:3], v0, off offset:1280
	v_cvt_pk_bf16_f32 v0, v24, v24
	global_store_short v[2:3], v0, off offset:1536
	v_cvt_pk_bf16_f32 v0, v26, v26
	global_store_short v[2:3], v0, off offset:1792
	v_cvt_pk_bf16_f32 v0, v28, v28
	global_store_short v[2:3], v0, off offset:2048
	v_cvt_pk_bf16_f32 v0, v30, v30
	global_store_short v[2:3], v0, off offset:2304
	v_cvt_pk_bf16_f32 v0, v64, v64
	global_store_short v[2:3], v0, off offset:2560
	v_cvt_pk_bf16_f32 v0, v65, v65
	global_store_short v[2:3], v0, off offset:2816
	v_cvt_pk_bf16_f32 v0, v66, v66
	global_store_short v[2:3], v0, off offset:3072
	v_cvt_pk_bf16_f32 v0, v68, v68
	global_store_short v[2:3], v0, off offset:3328
	v_cvt_pk_bf16_f32 v0, v69, v69
	global_store_short v[2:3], v0, off offset:3584
